# weight-conversion item tail: batched LDS u16 reads (rolling 15 outstanding), single 32-bit row*K address + scalar stride
# baseline (speedup 1.0000x reference)
.LBB0_465:
	s_or_b32 s23, s23, 7
	s_mulk_i32 s23, 0x214
	s_waitcnt vmcnt(0)
	v_mul_f32_e32 v2, v2, v10
	v_add_u32_e32 v6, s23, v38
	v_mul_f32_e32 v3, v3, v10
	v_cvt_pk_bf16_f32 v2, v2, v3
	ds_write_b32 v6, v2
	v_mul_f32_e32 v2, v4, v10
	v_mul_f32_e32 v3, v5, v10
	v_cvt_pk_bf16_f32 v2, v2, v3
	ds_write_b32 v6, v2 offset:4
	s_waitcnt lgkmcnt(0)
	s_barrier
	ds_read_u16 v48, v40
	ds_read_u16 v49, v40 offset:532
	ds_read_u16 v50, v40 offset:1064
	ds_read_u16 v51, v40 offset:1596
	ds_read_u16 v52, v40 offset:2128
	ds_read_u16 v53, v40 offset:2660
	ds_read_u16 v54, v40 offset:3192
	ds_read_u16 v55, v40 offset:3724
	ds_read_u16 v56, v40 offset:128
	ds_read_u16 v57, v40 offset:660
	ds_read_u16 v58, v40 offset:1192
	ds_read_u16 v59, v40 offset:1724
	ds_read_u16 v60, v40 offset:2256
	ds_read_u16 v61, v40 offset:2788
	ds_read_u16 v62, v40 offset:3320
	s_ashr_i32 s23, s22, 31
	v_add_u32_e32 v126, s58, v43
	v_lshl_add_u64 v[120:121], s[22:23], 1, v[34:35]
	v_mul_lo_u32 v122, v126, s48
	v_mov_b32_e32 v123, 0
	s_lshl_b32 s98, s48, 7
	s_mov_b32 s99, 0
	s_add_i32 s51, s51, s19
	v_add_u32_e32 v43, s55, v43
	v_add_u32_e32 v42, s55, v42
	v_add_u32_e32 v41, s57, v41
	v_lshl_add_u64 v[122:123], v[122:123], 1, v[120:121]
	s_waitcnt lgkmcnt(7)
	v_lshl_or_b32 v80, v49, 16, v48
	v_lshl_or_b32 v81, v51, 16, v50
	v_lshl_or_b32 v82, v53, 16, v52
	v_lshl_or_b32 v83, v55, 16, v54
	global_store_dwordx4 v[122:123], v[80:83], off
	v_lshl_add_u64 v[122:123], s[98:99], 0, v[122:123]
	ds_read_u16 v63, v40 offset:3852
	ds_read_u16 v64, v40 offset:256
	ds_read_u16 v65, v40 offset:788
	ds_read_u16 v66, v40 offset:1320
	ds_read_u16 v67, v40 offset:1852
	ds_read_u16 v68, v40 offset:2384
	ds_read_u16 v69, v40 offset:2916
	ds_read_u16 v70, v40 offset:3448
	s_waitcnt lgkmcnt(7)
	v_lshl_or_b32 v80, v57, 16, v56
	v_lshl_or_b32 v81, v59, 16, v58
	v_lshl_or_b32 v82, v61, 16, v60
	v_lshl_or_b32 v83, v63, 16, v62
	global_store_dwordx4 v[122:123], v[80:83], off
	v_lshl_add_u64 v[122:123], s[98:99], 0, v[122:123]
	ds_read_u16 v71, v40 offset:3980
	ds_read_u16 v72, v40 offset:384
	ds_read_u16 v73, v40 offset:916
	ds_read_u16 v74, v40 offset:1448
	ds_read_u16 v75, v40 offset:1980
	ds_read_u16 v76, v40 offset:2512
	ds_read_u16 v77, v40 offset:3044
	ds_read_u16 v78, v40 offset:3576
	s_waitcnt lgkmcnt(7)
	v_lshl_or_b32 v80, v65, 16, v64
	v_lshl_or_b32 v81, v67, 16, v66
	v_lshl_or_b32 v82, v69, 16, v68
	v_lshl_or_b32 v83, v71, 16, v70
	global_store_dwordx4 v[122:123], v[80:83], off
	v_lshl_add_u64 v[122:123], s[98:99], 0, v[122:123]
	ds_read_u16 v79, v40 offset:4108
	s_waitcnt lgkmcnt(0)
	v_lshl_or_b32 v80, v73, 16, v72
	v_lshl_or_b32 v81, v75, 16, v74
	v_lshl_or_b32 v82, v77, 16, v76
	v_lshl_or_b32 v83, v79, 16, v78
	global_store_dwordx4 v[122:123], v[80:83], off
	s_cmp_ge_i32 s51, s49
	s_barrier
	s_cbranch_scc1 .LBB0_441

.LBB0_557:
	s_or_b32 s23, s23, 7
	s_mulk_i32 s23, 0x214
	s_waitcnt vmcnt(0)
	v_mul_f32_e32 v2, v2, v10
	v_add_u32_e32 v6, s23, v38
	v_mul_f32_e32 v3, v3, v10
	v_cvt_pk_bf16_f32 v2, v2, v3
	ds_write_b32 v6, v2
	v_mul_f32_e32 v2, v4, v10
	v_mul_f32_e32 v3, v5, v10
	v_cvt_pk_bf16_f32 v2, v2, v3
	ds_write_b32 v6, v2 offset:4
	s_waitcnt lgkmcnt(0)
	s_barrier
	ds_read_u16 v48, v40
	ds_read_u16 v49, v40 offset:532
	ds_read_u16 v50, v40 offset:1064
	ds_read_u16 v51, v40 offset:1596
	ds_read_u16 v52, v40 offset:2128
	ds_read_u16 v53, v40 offset:2660
	ds_read_u16 v54, v40 offset:3192
	ds_read_u16 v55, v40 offset:3724
	ds_read_u16 v56, v40 offset:128
	ds_read_u16 v57, v40 offset:660
	ds_read_u16 v58, v40 offset:1192
	ds_read_u16 v59, v40 offset:1724
	ds_read_u16 v60, v40 offset:2256
	ds_read_u16 v61, v40 offset:2788
	ds_read_u16 v62, v40 offset:3320
	s_ashr_i32 s23, s22, 31
	v_add_u32_e32 v126, s59, v43
	v_lshl_add_u64 v[120:121], s[22:23], 1, v[34:35]
	v_mul_lo_u32 v122, v126, s49
	v_mov_b32_e32 v123, 0
	s_lshl_b32 s98, s49, 7
	s_mov_b32 s99, 0
	s_add_i32 s52, s52, s26
	v_add_u32_e32 v43, s56, v43
	v_add_u32_e32 v42, s56, v42
	v_add_u32_e32 v41, s58, v41
	v_lshl_add_u64 v[122:123], v[122:123], 1, v[120:121]
	s_waitcnt lgkmcnt(7)
	v_lshl_or_b32 v80, v49, 16, v48
	v_lshl_or_b32 v81, v51, 16, v50
	v_lshl_or_b32 v82, v53, 16, v52
	v_lshl_or_b32 v83, v55, 16, v54
	global_store_dwordx4 v[122:123], v[80:83], off
	v_lshl_add_u64 v[122:123], s[98:99], 0, v[122:123]
	ds_read_u16 v63, v40 offset:3852
	ds_read_u16 v64, v40 offset:256
	ds_read_u16 v65, v40 offset:788
	ds_read_u16 v66, v40 offset:1320
	ds_read_u16 v67, v40 offset:1852
	ds_read_u16 v68, v40 offset:2384
	ds_read_u16 v69, v40 offset:2916
	ds_read_u16 v70, v40 offset:3448
	s_waitcnt lgkmcnt(7)
	v_lshl_or_b32 v80, v57, 16, v56
	v_lshl_or_b32 v81, v59, 16, v58
	v_lshl_or_b32 v82, v61, 16, v60
	v_lshl_or_b32 v83, v63, 16, v62
	global_store_dwordx4 v[122:123], v[80:83], off
	v_lshl_add_u64 v[122:123], s[98:99], 0, v[122:123]
	ds_read_u16 v71, v40 offset:3980
	ds_read_u16 v72, v40 offset:384
	ds_read_u16 v73, v40 offset:916
	ds_read_u16 v74, v40 offset:1448
	ds_read_u16 v75, v40 offset:1980
	ds_read_u16 v76, v40 offset:2512
	ds_read_u16 v77, v40 offset:3044
	ds_read_u16 v78, v40 offset:3576
	s_waitcnt lgkmcnt(7)
	v_lshl_or_b32 v80, v65, 16, v64
	v_lshl_or_b32 v81, v67, 16, v66
	v_lshl_or_b32 v82, v69, 16, v68
	v_lshl_or_b32 v83, v71, 16, v70
	global_store_dwordx4 v[122:123], v[80:83], off
	v_lshl_add_u64 v[122:123], s[98:99], 0, v[122:123]
	ds_read_u16 v79, v40 offset:4108
	s_waitcnt lgkmcnt(0)
	v_lshl_or_b32 v80, v73, 16, v72
	v_lshl_or_b32 v81, v75, 16, v74
	v_lshl_or_b32 v82, v77, 16, v76
	v_lshl_or_b32 v83, v79, 16, v78
	global_store_dwordx4 v[122:123], v[80:83], off
	s_cmp_ge_i32 s52, s50
	s_barrier
	s_cbranch_scc1 .LBB0_533

.LBB0_620:
	s_or_b32 s15, s15, 7
	s_mulk_i32 s15, 0x214
	s_waitcnt vmcnt(0)
	v_mul_f32_e32 v2, v2, v10
	v_add_u32_e32 v6, s15, v39
	v_mul_f32_e32 v3, v3, v10
	v_cvt_pk_bf16_f32 v2, v2, v3
	ds_write_b32 v6, v2
	v_mul_f32_e32 v2, v4, v10
	v_mul_f32_e32 v3, v5, v10
	v_cvt_pk_bf16_f32 v2, v2, v3
	ds_write_b32 v6, v2 offset:4
	s_waitcnt lgkmcnt(0)
	s_barrier
	ds_read_u16 v48, v41
	ds_read_u16 v49, v41 offset:532
	ds_read_u16 v50, v41 offset:1064
	ds_read_u16 v51, v41 offset:1596
	ds_read_u16 v52, v41 offset:2128
	ds_read_u16 v53, v41 offset:2660
	ds_read_u16 v54, v41 offset:3192
	ds_read_u16 v55, v41 offset:3724
	ds_read_u16 v56, v41 offset:128
	ds_read_u16 v57, v41 offset:660
	ds_read_u16 v58, v41 offset:1192
	ds_read_u16 v59, v41 offset:1724
	ds_read_u16 v60, v41 offset:2256
	ds_read_u16 v61, v41 offset:2788
	ds_read_u16 v62, v41 offset:3320
	s_ashr_i32 s15, s14, 31
	v_add_u32_e32 v126, s51, v44
	v_lshl_add_u64 v[120:121], s[14:15], 1, v[36:37]
	v_mul_lo_u32 v122, v126, s31
	v_mov_b32_e32 v123, 0
	s_lshl_b32 s98, s31, 7
	s_mov_b32 s99, 0
	s_add_i32 s36, s36, s92
	v_add_u32_e32 v44, s48, v44
	v_add_u32_e32 v43, s48, v43
	v_add_u32_e32 v42, s50, v42
	v_lshl_add_u64 v[122:123], v[122:123], 1, v[120:121]
	s_waitcnt lgkmcnt(7)
	v_lshl_or_b32 v80, v49, 16, v48
	v_lshl_or_b32 v81, v51, 16, v50
	v_lshl_or_b32 v82, v53, 16, v52
	v_lshl_or_b32 v83, v55, 16, v54
	global_store_dwordx4 v[122:123], v[80:83], off
	v_lshl_add_u64 v[122:123], s[98:99], 0, v[122:123]
	ds_read_u16 v63, v41 offset:3852
	ds_read_u16 v64, v41 offset:256
	ds_read_u16 v65, v41 offset:788
	ds_read_u16 v66, v41 offset:1320
	ds_read_u16 v67, v41 offset:1852
	ds_read_u16 v68, v41 offset:2384
	ds_read_u16 v69, v41 offset:2916
	ds_read_u16 v70, v41 offset:3448
	s_waitcnt lgkmcnt(7)
	v_lshl_or_b32 v80, v57, 16, v56
	v_lshl_or_b32 v81, v59, 16, v58
	v_lshl_or_b32 v82, v61, 16, v60
	v_lshl_or_b32 v83, v63, 16, v62
	global_store_dwordx4 v[122:123], v[80:83], off
	v_lshl_add_u64 v[122:123], s[98:99], 0, v[122:123]
	ds_read_u16 v71, v41 offset:3980
	ds_read_u16 v72, v41 offset:384
	ds_read_u16 v73, v41 offset:916
	ds_read_u16 v74, v41 offset:1448
	ds_read_u16 v75, v41 offset:1980
	ds_read_u16 v76, v41 offset:2512
	ds_read_u16 v77, v41 offset:3044
	ds_read_u16 v78, v41 offset:3576
	s_waitcnt lgkmcnt(7)
	v_lshl_or_b32 v80, v65, 16, v64
	v_lshl_or_b32 v81, v67, 16, v66
	v_lshl_or_b32 v82, v69, 16, v68
	v_lshl_or_b32 v83, v71, 16, v70
	global_store_dwordx4 v[122:123], v[80:83], off
	v_lshl_add_u64 v[122:123], s[98:99], 0, v[122:123]
	ds_read_u16 v79, v41 offset:4108
	s_waitcnt lgkmcnt(0)
	v_lshl_or_b32 v80, v73, 16, v72
	v_lshl_or_b32 v81, v75, 16, v74
	v_lshl_or_b32 v82, v77, 16, v76
	v_lshl_or_b32 v83, v79, 16, v78
	global_store_dwordx4 v[122:123], v[80:83], off
	s_cmp_ge_i32 s36, s34
	s_barrier
	s_cbranch_scc1 .LBB0_596
